# v44 + K/V staging ds_writes and next-stage global prefetch loads spread over the MFMA shadows of slots 1 and 3 instead of one burst after slot 0
# speedup vs baseline: 1.0407x; 1.0032x over previous
.Latt_loop:
	s_add_i32 s13, s12, 1
	s_cmp_eq_u32 s12, 2
	s_cselect_b32 s12, 0, s13
	s_mul_i32 s15, s12, 0x4800
	s_mul_i32 s16, s12, 0x6000
	s_add_i32 s16, s16, 0xd800
	s_add_i32 s17, s14, 2
	s_min_u32 s17, s17, s11
	s_lshl_b32 s64, s17, 17
	s_add_u32 s18, s64, s83
	s_mov_b32 s19, 0
	s_add_i32 s14, s14, 1
	v_mov_b32_e32 v250, v251
	v_add3_u32 v251, s15, v236, v210
	v_mov_b32_e32 v252, v215
	v_add_u32_e32 v215, s16, v232
	s_waitcnt lgkmcnt(5)
	v_mfma_f32_32x32x16_bf16 v[98:113], v[238:241], v[134:137], 0
	v_exp_f32_e32 v66, v66
	v_exp_f32_e32 v67, v67
	v_exp_f32_e32 v68, v68
	ds_read_b128 v[238:241], v250 offset:4672
	v_mfma_f32_32x32x16_bf16 v[34:49], v[182:185], v[118:121], v[34:49]
	v_exp_f32_e32 v69, v69
	v_exp_f32_e32 v70, v70
	v_exp_f32_e32 v71, v71
	ds_read_b64_tr_b16 v[182:183], v252 offset:3072
	ds_read_b64_tr_b16 v[184:185], v252 offset:4608
	v_mfma_f32_32x32x16_bf16 v[50:65], v[186:189], v[118:121], v[50:65]
	v_exp_f32_e32 v72, v72
	v_exp_f32_e32 v73, v73
	v_cvt_pk_bf16_f32 v66, v66, v67
	v_cvt_pk_bf16_f32 v67, v68, v69
	ds_read_b64_tr_b16 v[186:187], v252 offset:3136
	ds_read_b64_tr_b16 v[188:189], v252 offset:4672
	v_mfma_f32_16x16x32_bf16 v[170:173], v[130:133], v[118:121], v[170:173]
	v_cvt_pk_bf16_f32 v68, v70, v71
	v_cvt_pk_bf16_f32 v69, v72, v73
	s_waitcnt lgkmcnt(5)
	v_mfma_f32_32x32x16_bf16 v[98:113], v[242:245], v[138:141], v[98:113]
	v_exp_f32_e32 v82, v82
	v_exp_f32_e32 v83, v83
	v_exp_f32_e32 v84, v84
	ds_read_b128 v[242:245], v250 offset:4704
	s_waitcnt vmcnt(0)
	v_add_u32_e32 v246, s15, v204
	v_add_u32_e32 v247, s16, v231
	ds_write_b128 v246, v[158:161]
	ds_write_b128 v246, v[162:165] offset:9216
	v_mfma_f32_32x32x16_bf16 v[2:17], v[174:177], v[66:69], v[2:17]
	v_exp_f32_e32 v85, v85
	v_exp_f32_e32 v86, v86
	v_exp_f32_e32 v87, v87
	ds_write_b128 v247, v[150:153]
	ds_write_b128 v247, v[154:157] offset:12288
	v_mfma_f32_32x32x16_bf16 v[18:33], v[178:181], v[66:69], v[18:33]
	v_exp_f32_e32 v88, v88
	v_exp_f32_e32 v89, v89
	v_cvt_pk_bf16_f32 v82, v82, v83
	v_cvt_pk_bf16_f32 v83, v84, v85
	s_add_u32 s18, s100, s64
	s_addc_u32 s19, s101, 0
	global_load_dwordx4 v[158:161], v248, s[18:19]
	global_load_dwordx4 v[162:165], v249, s[18:19]
	v_mfma_f32_16x16x32_bf16 v[166:169], v[130:133], v[66:69], v[166:169]
	v_cvt_pk_bf16_f32 v84, v86, v87
	v_cvt_pk_bf16_f32 v85, v88, v89
	s_waitcnt lgkmcnt(9)
	v_mfma_f32_32x32x16_bf16 v[114:129], v[238:241], v[142:145], 0
	v_exp_f32_e32 v74, v74
	v_exp_f32_e32 v75, v75
	v_exp_f32_e32 v76, v76
	ds_read_b128 v[238:241], v250 offset:9216
	v_mfma_f32_32x32x16_bf16 v[34:49], v[174:177], v[82:85], v[34:49]
	v_exp_f32_e32 v77, v77
	v_exp_f32_e32 v78, v78
	v_exp_f32_e32 v79, v79
	ds_read_b64_tr_b16 v[174:175], v252 offset:6144
	ds_read_b64_tr_b16 v[176:177], v252 offset:7680
	v_mfma_f32_32x32x16_bf16 v[50:65], v[178:181], v[82:85], v[50:65]
	v_exp_f32_e32 v80, v80
	v_exp_f32_e32 v81, v81
	v_cvt_pk_bf16_f32 v70, v74, v75
	v_cvt_pk_bf16_f32 v71, v76, v77
	ds_read_b64_tr_b16 v[178:179], v252 offset:6208
	ds_read_b64_tr_b16 v[180:181], v252 offset:7744
	v_mfma_f32_16x16x32_bf16 v[170:173], v[130:133], v[82:85], v[170:173]
	v_cvt_pk_bf16_f32 v72, v78, v79
	v_cvt_pk_bf16_f32 v73, v80, v81
	s_waitcnt lgkmcnt(9)
	v_mfma_f32_32x32x16_bf16 v[114:129], v[242:245], v[146:149], v[114:129]
	v_exp_f32_e32 v90, v90
	v_exp_f32_e32 v91, v91
	v_exp_f32_e32 v92, v92
	ds_read_b128 v[242:245], v250 offset:9248
	v_mfma_f32_32x32x16_bf16 v[2:17], v[182:185], v[70:73], v[2:17]
	v_exp_f32_e32 v93, v93
	v_exp_f32_e32 v94, v94
	v_exp_f32_e32 v95, v95
	s_add_u32 s18, s18, 0x1040000
	s_addc_u32 s19, s19, 0
	global_load_dwordx4 v[150:153], v248, s[18:19]
	global_load_dwordx4 v[154:157], v249, s[18:19]
	v_mfma_f32_32x32x16_bf16 v[18:33], v[186:189], v[70:73], v[18:33]
	v_exp_f32_e32 v96, v96
	v_exp_f32_e32 v97, v97
	v_cvt_pk_bf16_f32 v86, v90, v91
	v_cvt_pk_bf16_f32 v87, v92, v93
	v_mfma_f32_16x16x32_bf16 v[166:169], v[130:133], v[70:73], v[166:169]
	v_cvt_pk_bf16_f32 v88, v94, v95
	v_cvt_pk_bf16_f32 v89, v96, v97
	s_waitcnt lgkmcnt(5)
	v_mfma_f32_32x32x16_bf16 v[66:81], v[238:241], v[134:137], 0
	v_exp_f32_e32 v98, v98
	v_exp_f32_e32 v99, v99
	v_exp_f32_e32 v100, v100
	ds_read_b128 v[238:241], v250 offset:9280
	v_mfma_f32_32x32x16_bf16 v[34:49], v[182:185], v[86:89], v[34:49]
	v_exp_f32_e32 v101, v101
	v_exp_f32_e32 v102, v102
	v_exp_f32_e32 v103, v103
	ds_read_b64_tr_b16 v[182:183], v252 offset:9216
	ds_read_b64_tr_b16 v[184:185], v252 offset:10752
	v_mfma_f32_32x32x16_bf16 v[50:65], v[186:189], v[86:89], v[50:65]
	v_exp_f32_e32 v104, v104
	v_exp_f32_e32 v105, v105
	v_cvt_pk_bf16_f32 v98, v98, v99
	v_cvt_pk_bf16_f32 v99, v100, v101
	ds_read_b64_tr_b16 v[186:187], v252 offset:9280
	ds_read_b64_tr_b16 v[188:189], v252 offset:10816
	v_mfma_f32_16x16x32_bf16 v[170:173], v[130:133], v[86:89], v[170:173]
	v_cvt_pk_bf16_f32 v100, v102, v103
	v_cvt_pk_bf16_f32 v101, v104, v105
	s_waitcnt lgkmcnt(5)
	v_mfma_f32_32x32x16_bf16 v[66:81], v[242:245], v[138:141], v[66:81]
	v_exp_f32_e32 v114, v114
	v_exp_f32_e32 v115, v115
	v_exp_f32_e32 v116, v116
	ds_read_b128 v[242:245], v250 offset:9312
	v_mfma_f32_32x32x16_bf16 v[2:17], v[174:177], v[98:101], v[2:17]
	v_exp_f32_e32 v117, v117
	v_exp_f32_e32 v118, v118
	v_exp_f32_e32 v119, v119
	v_mfma_f32_32x32x16_bf16 v[18:33], v[178:181], v[98:101], v[18:33]
	v_exp_f32_e32 v120, v120
	v_exp_f32_e32 v121, v121
	v_cvt_pk_bf16_f32 v114, v114, v115
	v_cvt_pk_bf16_f32 v115, v116, v117
	v_mfma_f32_16x16x32_bf16 v[166:169], v[130:133], v[98:101], v[166:169]
	v_cvt_pk_bf16_f32 v116, v118, v119
	v_cvt_pk_bf16_f32 v117, v120, v121
	s_waitcnt lgkmcnt(5)
	v_mfma_f32_32x32x16_bf16 v[82:97], v[238:241], v[142:145], 0
	v_exp_f32_e32 v106, v106
	v_exp_f32_e32 v107, v107
	v_exp_f32_e32 v108, v108
	ds_read_b128 v[238:241], v250 offset:13824
	v_mfma_f32_32x32x16_bf16 v[34:49], v[174:177], v[114:117], v[34:49]
	v_exp_f32_e32 v109, v109
	v_exp_f32_e32 v110, v110
	v_exp_f32_e32 v111, v111
	ds_read_b64_tr_b16 v[174:175], v252 offset:12288
	ds_read_b64_tr_b16 v[176:177], v252 offset:13824
	v_mfma_f32_32x32x16_bf16 v[50:65], v[178:181], v[114:117], v[50:65]
	v_exp_f32_e32 v112, v112
	v_exp_f32_e32 v113, v113
	v_cvt_pk_bf16_f32 v102, v106, v107
	v_cvt_pk_bf16_f32 v103, v108, v109
	ds_read_b64_tr_b16 v[178:179], v252 offset:12352
	ds_read_b64_tr_b16 v[180:181], v252 offset:13888
	v_mfma_f32_16x16x32_bf16 v[170:173], v[130:133], v[114:117], v[170:173]
	v_cvt_pk_bf16_f32 v104, v110, v111
	v_cvt_pk_bf16_f32 v105, v112, v113
	s_waitcnt lgkmcnt(5)
	v_mfma_f32_32x32x16_bf16 v[82:97], v[242:245], v[146:149], v[82:97]
	v_exp_f32_e32 v122, v122
	v_exp_f32_e32 v123, v123
	v_exp_f32_e32 v124, v124
	ds_read_b128 v[242:245], v250 offset:13856
	v_mfma_f32_32x32x16_bf16 v[2:17], v[182:185], v[102:105], v[2:17]
	v_exp_f32_e32 v125, v125
	v_exp_f32_e32 v126, v126
	v_exp_f32_e32 v127, v127
	v_mfma_f32_32x32x16_bf16 v[18:33], v[186:189], v[102:105], v[18:33]
	v_exp_f32_e32 v128, v128
	v_exp_f32_e32 v129, v129
	v_cvt_pk_bf16_f32 v118, v122, v123
	v_cvt_pk_bf16_f32 v119, v124, v125
	v_mfma_f32_16x16x32_bf16 v[166:169], v[130:133], v[102:105], v[166:169]
	v_cvt_pk_bf16_f32 v120, v126, v127
	v_cvt_pk_bf16_f32 v121, v128, v129
	s_waitcnt lgkmcnt(5)
	v_mfma_f32_32x32x16_bf16 v[98:113], v[238:241], v[134:137], 0
	v_exp_f32_e32 v66, v66
	v_exp_f32_e32 v67, v67
	v_exp_f32_e32 v68, v68
	ds_read_b128 v[238:241], v250 offset:13888
	v_mfma_f32_32x32x16_bf16 v[34:49], v[182:185], v[118:121], v[34:49]
	v_exp_f32_e32 v69, v69
	v_exp_f32_e32 v70, v70
	v_exp_f32_e32 v71, v71
	ds_read_b64_tr_b16 v[182:183], v252 offset:15360
	ds_read_b64_tr_b16 v[184:185], v252 offset:16896
	v_mfma_f32_32x32x16_bf16 v[50:65], v[186:189], v[118:121], v[50:65]
	v_exp_f32_e32 v72, v72
	v_exp_f32_e32 v73, v73
	v_cvt_pk_bf16_f32 v66, v66, v67
	v_cvt_pk_bf16_f32 v67, v68, v69
	ds_read_b64_tr_b16 v[186:187], v252 offset:15424
	ds_read_b64_tr_b16 v[188:189], v252 offset:16960
	v_mfma_f32_16x16x32_bf16 v[170:173], v[130:133], v[118:121], v[170:173]
	v_cvt_pk_bf16_f32 v68, v70, v71
	v_cvt_pk_bf16_f32 v69, v72, v73
	s_waitcnt lgkmcnt(5)
	v_mfma_f32_32x32x16_bf16 v[98:113], v[242:245], v[138:141], v[98:113]
	v_exp_f32_e32 v82, v82
	v_exp_f32_e32 v83, v83
	v_exp_f32_e32 v84, v84
	ds_read_b128 v[242:245], v250 offset:13920
	v_mfma_f32_32x32x16_bf16 v[2:17], v[174:177], v[66:69], v[2:17]
	v_exp_f32_e32 v85, v85
	v_exp_f32_e32 v86, v86
	v_exp_f32_e32 v87, v87
	v_mfma_f32_32x32x16_bf16 v[18:33], v[178:181], v[66:69], v[18:33]
	v_exp_f32_e32 v88, v88
	v_exp_f32_e32 v89, v89
	v_cvt_pk_bf16_f32 v82, v82, v83
	v_cvt_pk_bf16_f32 v83, v84, v85
	v_mfma_f32_16x16x32_bf16 v[166:169], v[130:133], v[66:69], v[166:169]
	v_cvt_pk_bf16_f32 v84, v86, v87
	v_cvt_pk_bf16_f32 v85, v88, v89
	s_barrier
	s_waitcnt lgkmcnt(5)
	v_mfma_f32_32x32x16_bf16 v[114:129], v[238:241], v[142:145], 0
	v_exp_f32_e32 v74, v74
	v_exp_f32_e32 v75, v75
	v_exp_f32_e32 v76, v76
	ds_read_b128 v[238:241], v251
	v_mfma_f32_32x32x16_bf16 v[34:49], v[174:177], v[82:85], v[34:49]
	v_exp_f32_e32 v77, v77
	v_exp_f32_e32 v78, v78
	v_exp_f32_e32 v79, v79
	ds_read_b64_tr_b16 v[174:175], v252 offset:18432
	ds_read_b64_tr_b16 v[176:177], v252 offset:19968
	v_mfma_f32_32x32x16_bf16 v[50:65], v[178:181], v[82:85], v[50:65]
	v_exp_f32_e32 v80, v80
	v_exp_f32_e32 v81, v81
	v_cvt_pk_bf16_f32 v70, v74, v75
	v_cvt_pk_bf16_f32 v71, v76, v77
	ds_read_b64_tr_b16 v[178:179], v252 offset:18496
	ds_read_b64_tr_b16 v[180:181], v252 offset:20032
	v_mfma_f32_16x16x32_bf16 v[170:173], v[130:133], v[82:85], v[170:173]
	v_cvt_pk_bf16_f32 v72, v78, v79
	v_cvt_pk_bf16_f32 v73, v80, v81
	s_waitcnt lgkmcnt(5)
	v_mfma_f32_32x32x16_bf16 v[114:129], v[242:245], v[146:149], v[114:129]
	v_exp_f32_e32 v90, v90
	v_exp_f32_e32 v91, v91
	v_exp_f32_e32 v92, v92
	ds_read_b128 v[242:245], v251 offset:32
	v_mfma_f32_32x32x16_bf16 v[2:17], v[182:185], v[70:73], v[2:17]
	v_exp_f32_e32 v93, v93
	v_exp_f32_e32 v94, v94
	v_exp_f32_e32 v95, v95
	v_mfma_f32_32x32x16_bf16 v[18:33], v[186:189], v[70:73], v[18:33]
	v_exp_f32_e32 v96, v96
	v_exp_f32_e32 v97, v97
	v_cvt_pk_bf16_f32 v86, v90, v91
	v_cvt_pk_bf16_f32 v87, v92, v93
	v_mfma_f32_16x16x32_bf16 v[166:169], v[130:133], v[70:73], v[166:169]
	v_cvt_pk_bf16_f32 v88, v94, v95
	v_cvt_pk_bf16_f32 v89, v96, v97
	s_waitcnt lgkmcnt(5)
	v_mfma_f32_32x32x16_bf16 v[66:81], v[238:241], v[134:137], 0
	v_exp_f32_e32 v98, v98
	v_exp_f32_e32 v99, v99
	v_exp_f32_e32 v100, v100
	ds_read_b128 v[238:241], v251 offset:64
	v_mfma_f32_32x32x16_bf16 v[34:49], v[182:185], v[86:89], v[34:49]
	v_exp_f32_e32 v101, v101
	v_exp_f32_e32 v102, v102
	v_exp_f32_e32 v103, v103
	ds_read_b64_tr_b16 v[182:183], v252 offset:21504
	ds_read_b64_tr_b16 v[184:185], v252 offset:23040
	v_mfma_f32_32x32x16_bf16 v[50:65], v[186:189], v[86:89], v[50:65]
	v_exp_f32_e32 v104, v104
	v_exp_f32_e32 v105, v105
	v_cvt_pk_bf16_f32 v98, v98, v99
	v_cvt_pk_bf16_f32 v99, v100, v101
	ds_read_b64_tr_b16 v[186:187], v252 offset:21568
	ds_read_b64_tr_b16 v[188:189], v252 offset:23104
	v_mfma_f32_16x16x32_bf16 v[170:173], v[130:133], v[86:89], v[170:173]
	v_cvt_pk_bf16_f32 v100, v102, v103
	v_cvt_pk_bf16_f32 v101, v104, v105
	s_waitcnt lgkmcnt(5)
	v_mfma_f32_32x32x16_bf16 v[66:81], v[242:245], v[138:141], v[66:81]
	v_exp_f32_e32 v114, v114
	v_exp_f32_e32 v115, v115
	v_exp_f32_e32 v116, v116
	ds_read_b128 v[242:245], v251 offset:96
	v_mfma_f32_32x32x16_bf16 v[2:17], v[174:177], v[98:101], v[2:17]
	v_exp_f32_e32 v117, v117
	v_exp_f32_e32 v118, v118
	v_exp_f32_e32 v119, v119
	v_mfma_f32_32x32x16_bf16 v[18:33], v[178:181], v[98:101], v[18:33]
	v_exp_f32_e32 v120, v120
	v_exp_f32_e32 v121, v121
	v_cvt_pk_bf16_f32 v114, v114, v115
	v_cvt_pk_bf16_f32 v115, v116, v117
	v_mfma_f32_16x16x32_bf16 v[166:169], v[130:133], v[98:101], v[166:169]
	v_cvt_pk_bf16_f32 v116, v118, v119
	v_cvt_pk_bf16_f32 v117, v120, v121
	s_waitcnt lgkmcnt(5)
	v_mfma_f32_32x32x16_bf16 v[82:97], v[238:241], v[142:145], 0
	v_exp_f32_e32 v106, v106
	v_exp_f32_e32 v107, v107
	v_exp_f32_e32 v108, v108
	ds_read_b128 v[238:241], v251 offset:4608
	v_mfma_f32_32x32x16_bf16 v[34:49], v[174:177], v[114:117], v[34:49]
	v_exp_f32_e32 v109, v109
	v_exp_f32_e32 v110, v110
	v_exp_f32_e32 v111, v111
	ds_read_b64_tr_b16 v[174:175], v215
	ds_read_b64_tr_b16 v[176:177], v215 offset:1536
	v_mfma_f32_32x32x16_bf16 v[50:65], v[178:181], v[114:117], v[50:65]
	v_exp_f32_e32 v112, v112
	v_exp_f32_e32 v113, v113
	v_cvt_pk_bf16_f32 v102, v106, v107
	v_cvt_pk_bf16_f32 v103, v108, v109
	ds_read_b64_tr_b16 v[178:179], v215 offset:64
	ds_read_b64_tr_b16 v[180:181], v215 offset:1600
	v_mfma_f32_16x16x32_bf16 v[170:173], v[130:133], v[114:117], v[170:173]
	v_cvt_pk_bf16_f32 v104, v110, v111
	v_cvt_pk_bf16_f32 v105, v112, v113
	s_waitcnt lgkmcnt(5)
	v_mfma_f32_32x32x16_bf16 v[82:97], v[242:245], v[146:149], v[82:97]
	v_exp_f32_e32 v122, v122
	v_exp_f32_e32 v123, v123
	v_exp_f32_e32 v124, v124
	ds_read_b128 v[242:245], v251 offset:4640
	v_mfma_f32_32x32x16_bf16 v[2:17], v[182:185], v[102:105], v[2:17]
	v_exp_f32_e32 v125, v125
	v_exp_f32_e32 v126, v126
	v_exp_f32_e32 v127, v127
	v_mfma_f32_32x32x16_bf16 v[18:33], v[186:189], v[102:105], v[18:33]
	v_exp_f32_e32 v128, v128
	v_exp_f32_e32 v129, v129
	v_cvt_pk_bf16_f32 v118, v122, v123
	v_cvt_pk_bf16_f32 v119, v124, v125
	v_mfma_f32_16x16x32_bf16 v[166:169], v[130:133], v[102:105], v[166:169]
	v_cvt_pk_bf16_f32 v120, v126, v127
	v_cvt_pk_bf16_f32 v121, v128, v129
	s_cmp_lg_u32 s14, s10
	s_cbranch_scc1 .Latt_loop
	s_waitcnt lgkmcnt(0)
	s_nop 1
	v_mfma_f32_16x16x32_bf16 v[170:173], v[130:133], v[118:121], v[170:173]
	v_mfma_f32_32x32x16_bf16 v[34:49], v[182:185], v[118:121], v[34:49]
	v_mfma_f32_32x32x16_bf16 v[50:65], v[186:189], v[118:121], v[50:65]
	s_nop 11
	global_load_dwordx4 v[98:101], v[212:213], off offset:32
	global_load_dwordx4 v[102:105], v[212:213], off offset:64
	global_load_dwordx4 v[106:109], v[212:213], off offset:96
	global_load_dwordx4 v[110:113], v[212:213], off offset:128
	global_load_dwordx4 v[114:117], v[212:213], off offset:160
	global_load_dwordx4 v[122:125], v[212:213], off offset:192
	global_load_dwordx4 v[126:129], v[212:213], off offset:224
	ds_bpermute_b32 v66, v237, v166
	s_nop 3
	ds_bpermute_b32 v67, v237, v170
	s_lshl_b32 s64, s9, 1
	v_mov_b32_e32 v215, v191
	s_mov_b32 s2, 0xf226000
	s_waitcnt lgkmcnt(1)
	v_div_scale_f32 v68, s[10:11], v66, v66, 1.0
	v_rcp_f32_e32 v69, v68
	s_add_i32 s8, s8, 1
	s_cmp_eq_u32 s8, s7
	v_fma_f32 v70, -v68, v69, 1.0
	v_fmac_f32_e32 v69, v70, v69
	v_div_scale_f32 v70, vcc, 1.0, v66, 1.0
	v_mul_f32_e32 v71, v70, v69
	v_fma_f32 v72, -v68, v71, v70
	v_fmac_f32_e32 v71, v72, v69
	v_fma_f32 v68, -v68, v71, v70
	v_div_fmas_f32 v68, v68, v69, v71
	v_div_fixup_f32 v66, v68, v66, 1.0
	s_waitcnt lgkmcnt(0)
	v_div_scale_f32 v68, s[10:11], v67, v67, v230
	v_rcp_f32_e32 v69, v68
	s_mov_b64 s[10:11], 0xf226400
	v_fma_f32 v70, -v68, v69, 1.0
	v_fmac_f32_e32 v69, v70, v69
	v_div_scale_f32 v70, vcc, v230, v67, v230
	v_mul_f32_e32 v71, v70, v69
	v_fma_f32 v72, -v68, v71, v70
	v_fmac_f32_e32 v71, v72, v69
	v_fma_f32 v68, -v68, v71, v70
	v_div_fmas_f32 v68, v68, v69, v71
	v_div_fixup_f32 v68, v68, v67, v230
	v_pk_mul_f32 v[62:63], v[62:63], v[68:69] op_sel_hi:[1,0]
	v_pk_mul_f32 v[34:35], v[34:35], v[68:69] op_sel_hi:[1,0]
	v_pk_fma_f32 v[30:31], v[30:31], v[66:67], v[62:63] op_sel_hi:[1,0,1] neg_lo:[0,0,1] neg_hi:[0,0,1]
	v_pk_mul_f32 v[62:63], v[64:65], v[68:69] op_sel_hi:[1,0]
	v_pk_mul_f32 v[36:37], v[36:37], v[68:69] op_sel_hi:[1,0]
	v_pk_fma_f32 v[32:33], v[32:33], v[66:67], v[62:63] op_sel_hi:[1,0,1] neg_lo:[0,0,1] neg_hi:[0,0,1]
	v_lshlrev_b64 v[62:63], 11, v[216:217]
	v_lshl_add_u64 v[62:63], s[54:55], 0, v[62:63]
	v_lshl_add_u64 v[74:75], v[62:63], 0, s[64:65]
	global_load_dwordx4 v[62:65], v[212:213], off
	v_pk_fma_f32 v[34:35], v[2:3], v[66:67], v[34:35] op_sel_hi:[1,0,1] neg_lo:[0,0,1] neg_hi:[0,0,1]
	v_pk_fma_f32 v[4:5], v[4:5], v[66:67], v[36:37] op_sel_hi:[1,0,1] neg_lo:[0,0,1] neg_hi:[0,0,1]
	v_pk_mul_f32 v[76:77], v[34:35], v[34:35]
	v_pk_mul_f32 v[40:41], v[40:41], v[68:69] op_sel_hi:[1,0]
	v_pk_mul_f32 v[38:39], v[38:39], v[68:69] op_sel_hi:[1,0]
	v_pk_mul_f32 v[44:45], v[44:45], v[68:69] op_sel_hi:[1,0]
	v_pk_mul_f32 v[42:43], v[42:43], v[68:69] op_sel_hi:[1,0]
	v_pk_mul_f32 v[48:49], v[48:49], v[68:69] op_sel_hi:[1,0]
	v_pk_mul_f32 v[46:47], v[46:47], v[68:69] op_sel_hi:[1,0]
	v_pk_mul_f32 v[52:53], v[52:53], v[68:69] op_sel_hi:[1,0]
	v_pk_mul_f32 v[50:51], v[50:51], v[68:69] op_sel_hi:[1,0]
	v_pk_mul_f32 v[56:57], v[56:57], v[68:69] op_sel_hi:[1,0]
	v_pk_mul_f32 v[54:55], v[54:55], v[68:69] op_sel_hi:[1,0]
	v_pk_mul_f32 v[60:61], v[60:61], v[68:69] op_sel_hi:[1,0]
	v_pk_mul_f32 v[58:59], v[58:59], v[68:69] op_sel_hi:[1,0]
	v_pk_mul_f32 v[36:37], v[4:5], v[4:5]
	v_pk_fma_f32 v[8:9], v[8:9], v[66:67], v[40:41] op_sel_hi:[1,0,1] neg_lo:[0,0,1] neg_hi:[0,0,1]
	v_pk_fma_f32 v[38:39], v[6:7], v[66:67], v[38:39] op_sel_hi:[1,0,1] neg_lo:[0,0,1] neg_hi:[0,0,1]
	v_pk_fma_f32 v[12:13], v[12:13], v[66:67], v[44:45] op_sel_hi:[1,0,1] neg_lo:[0,0,1] neg_hi:[0,0,1]
	v_pk_fma_f32 v[10:11], v[10:11], v[66:67], v[42:43] op_sel_hi:[1,0,1] neg_lo:[0,0,1] neg_hi:[0,0,1]
	v_pk_fma_f32 v[16:17], v[16:17], v[66:67], v[48:49] op_sel_hi:[1,0,1] neg_lo:[0,0,1] neg_hi:[0,0,1]
	v_pk_fma_f32 v[14:15], v[14:15], v[66:67], v[46:47] op_sel_hi:[1,0,1] neg_lo:[0,0,1] neg_hi:[0,0,1]
	v_pk_fma_f32 v[20:21], v[20:21], v[66:67], v[52:53] op_sel_hi:[1,0,1] neg_lo:[0,0,1] neg_hi:[0,0,1]
	v_pk_fma_f32 v[18:19], v[18:19], v[66:67], v[50:51] op_sel_hi:[1,0,1] neg_lo:[0,0,1] neg_hi:[0,0,1]
	v_pk_fma_f32 v[24:25], v[24:25], v[66:67], v[56:57] op_sel_hi:[1,0,1] neg_lo:[0,0,1] neg_hi:[0,0,1]
	v_pk_fma_f32 v[22:23], v[22:23], v[66:67], v[54:55] op_sel_hi:[1,0,1] neg_lo:[0,0,1] neg_hi:[0,0,1]
	v_pk_fma_f32 v[28:29], v[28:29], v[66:67], v[60:61] op_sel_hi:[1,0,1] neg_lo:[0,0,1] neg_hi:[0,0,1]
	v_pk_fma_f32 v[26:27], v[26:27], v[66:67], v[58:59] op_sel_hi:[1,0,1] neg_lo:[0,0,1] neg_hi:[0,0,1]
	v_add_f32_e32 v66, v76, v77
	v_add_f32_e32 v36, v36, v66
	v_pk_mul_f32 v[6:7], v[38:39], v[38:39]
	v_add_f32_e32 v36, v37, v36
	v_add_f32_e32 v6, v6, v36
	v_pk_mul_f32 v[40:41], v[8:9], v[8:9]
	v_add_f32_e32 v6, v7, v6
	v_add_f32_e32 v6, v40, v6
	v_pk_mul_f32 v[42:43], v[10:11], v[10:11]
	v_add_f32_e32 v6, v41, v6
	v_add_f32_e32 v6, v42, v6
	v_pk_mul_f32 v[44:45], v[12:13], v[12:13]
	v_add_f32_e32 v6, v43, v6
	v_add_f32_e32 v6, v44, v6
	v_pk_mul_f32 v[46:47], v[14:15], v[14:15]
	v_add_f32_e32 v6, v45, v6
	v_add_f32_e32 v6, v46, v6
	v_pk_mul_f32 v[48:49], v[16:17], v[16:17]
	v_add_f32_e32 v6, v47, v6
	v_add_f32_e32 v6, v48, v6
	v_pk_mul_f32 v[50:51], v[18:19], v[18:19]
	v_add_f32_e32 v6, v49, v6
	v_add_f32_e32 v6, v50, v6
	v_pk_mul_f32 v[52:53], v[20:21], v[20:21]
	v_add_f32_e32 v6, v51, v6
	v_add_f32_e32 v6, v52, v6
	v_pk_mul_f32 v[54:55], v[22:23], v[22:23]
	v_add_f32_e32 v6, v53, v6
	v_add_f32_e32 v6, v54, v6
	v_pk_mul_f32 v[56:57], v[24:25], v[24:25]
	v_add_f32_e32 v6, v55, v6
	v_add_f32_e32 v6, v56, v6
	v_pk_mul_f32 v[58:59], v[26:27], v[26:27]
	v_add_f32_e32 v6, v57, v6
	v_add_f32_e32 v6, v58, v6
	v_pk_mul_f32 v[60:61], v[28:29], v[28:29]
	v_add_f32_e32 v6, v59, v6
	v_add_f32_e32 v6, v60, v6
	v_pk_mul_f32 v[70:71], v[30:31], v[30:31]
	v_add_f32_e32 v6, v61, v6
	v_add_f32_e32 v6, v70, v6
	v_pk_mul_f32 v[72:73], v[32:33], v[32:33]
	v_add_f32_e32 v6, v71, v6
	v_add_f32_e32 v6, v72, v6
	v_add_f32_e32 v6, v73, v6
	ds_bpermute_b32 v7, v229, v6
	v_lshl_add_u64 v[74:75], v[74:75], 0, v[214:215]
	v_lshl_add_u64 v[2:3], v[74:75], 0, s[10:11]
	s_waitcnt lgkmcnt(0)
	v_add_f32_e32 v6, v6, v7
	v_fmamk_f32 v6, v6, 0x3c800000, v192
	v_cmp_gt_f32_e32 vcc, s70, v6
	v_mul_f32_e32 v7, 0x4b800000, v6
	s_nop 0
	v_cndmask_b32_e32 v6, v6, v7, vcc
	v_rsq_f32_e32 v6, v6
	s_nop 0
	v_mul_f32_e32 v7, 0x45800000, v6
	v_cndmask_b32_e32 v6, v6, v7, vcc
	v_mul_f32_e32 v36, v233, v6
	v_pk_mul_f32 v[6:7], v[34:35], v[36:37] op_sel_hi:[1,0]
	v_pk_mul_f32 v[4:5], v[4:5], v[36:37] op_sel_hi:[1,0]
	s_waitcnt vmcnt(0)
	v_pk_mul_f32 v[6:7], v[62:63], v[6:7]
	v_pk_mul_f32 v[4:5], v[64:65], v[4:5]
	v_cvt_pk_bf16_f32 v6, v6, v7
	v_cvt_pk_bf16_f32 v7, v4, v5
	v_add_co_u32_e32 v4, vcc, s2, v74
	v_pk_mul_f32 v[34:35], v[38:39], v[36:37] op_sel_hi:[1,0]
	s_nop 0
	v_addc_co_u32_e32 v5, vcc, 0, v75, vcc
	global_store_dwordx2 v[4:5], v[6:7], off offset:1024
	v_pk_mul_f32 v[8:9], v[8:9], v[36:37] op_sel_hi:[1,0]
	v_mov_b64_e32 v[4:5], v[98:99]
	v_mov_b64_e32 v[6:7], v[100:101]
	v_pk_mul_f32 v[4:5], v[4:5], v[34:35]
	v_pk_mul_f32 v[6:7], v[6:7], v[8:9]
	v_cvt_pk_bf16_f32 v4, v4, v5
	v_cvt_pk_bf16_f32 v5, v6, v7
	global_store_dwordx2 v[2:3], v[4:5], off offset:16
	v_pk_mul_f32 v[8:9], v[10:11], v[36:37] op_sel_hi:[1,0]
	v_mov_b64_e32 v[4:5], v[102:103]
	v_mov_b64_e32 v[6:7], v[104:105]
	v_pk_mul_f32 v[4:5], v[4:5], v[8:9]
	v_pk_mul_f32 v[8:9], v[12:13], v[36:37] op_sel_hi:[1,0]
	v_cvt_pk_bf16_f32 v4, v4, v5
	v_pk_mul_f32 v[6:7], v[6:7], v[8:9]
	v_pk_mul_f32 v[8:9], v[14:15], v[36:37] op_sel_hi:[1,0]
	v_cvt_pk_bf16_f32 v5, v6, v7
	global_store_dwordx2 v[2:3], v[4:5], off offset:32
	v_mov_b64_e32 v[4:5], v[106:107]
	v_mov_b64_e32 v[6:7], v[108:109]
	v_pk_mul_f32 v[4:5], v[4:5], v[8:9]
	v_pk_mul_f32 v[8:9], v[16:17], v[36:37] op_sel_hi:[1,0]
	v_cvt_pk_bf16_f32 v4, v4, v5
	v_pk_mul_f32 v[6:7], v[6:7], v[8:9]
	v_pk_mul_f32 v[8:9], v[18:19], v[36:37] op_sel_hi:[1,0]
	v_cvt_pk_bf16_f32 v5, v6, v7
	global_store_dwordx2 v[2:3], v[4:5], off offset:48
	v_mov_b64_e32 v[4:5], v[110:111]
	v_mov_b64_e32 v[6:7], v[112:113]
	v_pk_mul_f32 v[4:5], v[4:5], v[8:9]
	v_pk_mul_f32 v[8:9], v[20:21], v[36:37] op_sel_hi:[1,0]
	v_cvt_pk_bf16_f32 v4, v4, v5
	v_pk_mul_f32 v[6:7], v[6:7], v[8:9]
	v_pk_mul_f32 v[8:9], v[22:23], v[36:37] op_sel_hi:[1,0]
	v_cvt_pk_bf16_f32 v5, v6, v7
	global_store_dwordx2 v[2:3], v[4:5], off offset:64
	v_mov_b64_e32 v[4:5], v[114:115]
	v_mov_b64_e32 v[6:7], v[116:117]
	v_pk_mul_f32 v[4:5], v[4:5], v[8:9]
	v_pk_mul_f32 v[8:9], v[24:25], v[36:37] op_sel_hi:[1,0]
	v_cvt_pk_bf16_f32 v4, v4, v5
	v_pk_mul_f32 v[6:7], v[6:7], v[8:9]
	v_pk_mul_f32 v[8:9], v[26:27], v[36:37] op_sel_hi:[1,0]
	v_cvt_pk_bf16_f32 v5, v6, v7
	global_store_dwordx2 v[2:3], v[4:5], off offset:80
	v_mov_b64_e32 v[4:5], v[122:123]
	v_mov_b64_e32 v[6:7], v[124:125]
	v_pk_mul_f32 v[4:5], v[4:5], v[8:9]
	v_pk_mul_f32 v[8:9], v[28:29], v[36:37] op_sel_hi:[1,0]
	v_cvt_pk_bf16_f32 v4, v4, v5
	v_pk_mul_f32 v[6:7], v[6:7], v[8:9]
	v_pk_mul_f32 v[8:9], v[30:31], v[36:37] op_sel_hi:[1,0]
	v_cvt_pk_bf16_f32 v5, v6, v7
	global_store_dwordx2 v[2:3], v[4:5], off offset:96
	v_mov_b64_e32 v[4:5], v[126:127]
	v_mov_b64_e32 v[6:7], v[128:129]
	v_pk_mul_f32 v[4:5], v[4:5], v[8:9]
	v_pk_mul_f32 v[8:9], v[32:33], v[36:37] op_sel_hi:[1,0]
	v_cvt_pk_bf16_f32 v4, v4, v5
	v_pk_mul_f32 v[6:7], v[6:7], v[8:9]
	s_nop 0
	v_cvt_pk_bf16_f32 v5, v6, v7
	global_store_dwordx2 v[2:3], v[4:5], off offset:112
	s_cbranch_scc0 .LBB0_745
